# k=6: workgroups 96+ run the next layer's weight conversion before their merge GEMMs (staggers epilogue traffic)
# baseline (speedup 1.0000x reference)
; #define LAS __attribute__((address_space(3)))
; __device__ __forceinline__ unsigned xb_ld(unsigned* p)              { return __hip_atomic_load(p, __ATOMIC_RELAXED, __HIP_MEMORY_SCOPE_AGENT); }
; __device__ __forceinline__ XcdBarrier xcd_barrier_post(unsigned* bar, volatile LAS unsigned* st) {
;     XcdBarrier b; b.bar = bar; b.x = xb_xcc_id(); b.st = st;
;     if (threadIdx.x == 0) (void)xb_add(&bar[XB_XCNT(b.x)], 1u);
;     return b;
; }
; __device__ __forceinline__ void xcd_barrier_complete(unsigned* bar, unsigned x, unsigned& nloc, unsigned& nx) {
;     const unsigned G = gridDim.x * gridDim.y * gridDim.z;
;     unsigned sum, cnt, mine, sp = 0u;
;     for (;;) {
;         sum = 0u; cnt = 0u; mine = 0u;
; #pragma unroll
;         for (unsigned j = 0; j < 16; ++j) { const unsigned c = xb_ld(&bar[XB_XCNT(j)]); sum += c; cnt += (c > 0u) ? 1u : 0u; mine = (j == x) ? c : mine; }
;         if (sum == G) break;
;         __builtin_amdgcn_s_sleep(1);
;         if ((++sp & 255u) == 0u) { if (xb_ld(&bar[XB_TMO])) break; if (sp > XB_SPIN_CAP) { atomicAdd(&bar[XB_TMO], 1u); break; } }
;     }
;     nloc = mine > 0u ? mine : 1u; nx = cnt > 0u ? cnt : 1u;
; }
; __global__ void __launch_bounds__(512, 2) mega_fwd(Args a_) {
;     ...
;     const int ph_lo = a_.lo, ph_hi = a_.hi;
;     volatile LAS unsigned* bst = (volatile LAS unsigned*)((LAS unsigned char*)lds + 131072);
;     if (threadIdx.x < 2) bst[threadIdx.x] = 0u;
;     __syncthreads();
;     const XcdBarrier xbar = xcd_barrier_post((unsigned*)(a_.ws + WS_BAR), bst);
;     const int wave_s = __builtin_amdgcn_readfirstlane((int)threadIdx.x >> 6);
; #pragma nounroll
;     for (int ph = ph_lo; ph < ph_hi; ++ph) {
;         CArgs* ap = (CArgs*)__builtin_amdgcn_kernarg_segment_ptr(); asm volatile("" : "+s"(ap));
;         CArgs& a = *ap;
;         unsigned char* ws = a.ws;
;         float* XC = (float*)(ws + WS_XC);
;         int wsv = wave_s; asm volatile("" : "+s"(wsv));
;         TI ti; ti.tid = wsv * 64 + (int)__builtin_amdgcn_mbcnt_hi(~0u, __builtin_amdgcn_mbcnt_lo(~0u, 0u)); ti.bid = blockIdx.x; ti.nblk = gridDim.x;
;         asm volatile("" : "+v"(ti.tid)); asm volatile("" : "+s"(ti.bid)); asm volatile("" : "+s"(ti.nblk));
;         const int tid = ti.tid, lane = tid & 63, wv = __builtin_amdgcn_readfirstlane(tid >> 6);
;         const int gw = ti.bid * 8 + wv, ngw = ti.nblk * 8;
.LBB0_6:
	s_lshr_b32 s2, s2, 6
	v_writelane_b32 v254, s2, 8
	v_lshrrev_b32_e32 v2, 20, v0
	v_readlane_b32 s2, v254, 0
	v_readlane_b32 s4, v254, 2
	v_readlane_b32 s3, v254, 1
	v_readlane_b32 s5, v254, 3
	s_mul_i32 s2, s3, s2
	s_load_dword s3, s[4:5], 0x128
	v_lshrrev_b32_e32 v0, 10, v0
	v_or_b32_e32 v0, v0, v2
	s_mov_b32 s10, s58
	v_mov_b32_e32 v172, 0x358637bd
	s_waitcnt lgkmcnt(0)
	s_mul_i32 s18, s2, s3
	s_add_u32 s2, s56, 0xe0200
	s_addc_u32 s3, s57, 0
	s_add_u32 s36, s56, 0xe0400
	s_addc_u32 s37, s57, 0
	s_add_u32 s60, s56, 0xe0500
	s_addc_u32 s61, s57, 0
	s_add_u32 s62, s56, 0xe0600
	s_addc_u32 s63, s57, 0
	s_add_u32 s66, s56, 0xe0700
	s_addc_u32 s67, s57, 0
	s_add_u32 s72, s56, 0xe0800
	s_addc_u32 s73, s57, 0
	s_add_u32 s76, s56, 0xe0900
	s_addc_u32 s77, s57, 0
	s_add_u32 s80, s56, 0xe0a00
	s_addc_u32 s81, s57, 0
	s_add_u32 s84, s56, 0xe0b00
	s_addc_u32 s85, s57, 0
	s_add_u32 s86, s56, 0xe0c00
	s_addc_u32 s87, s57, 0
	s_add_u32 s88, s56, 0xe0d00
	s_addc_u32 s89, s57, 0
	s_add_u32 s90, s56, 0xe0e00
	s_addc_u32 s91, s57, 0
	s_add_u32 s94, s56, 0xe0f00
	v_writelane_b32 v254, s2, 9
	s_addc_u32 s95, s57, 0
	v_mov_b32_e32 v186, 0x3ca908c9
	v_writelane_b32 v254, s3, 10
	s_add_u32 s2, s56, 0xe1000
	s_addc_u32 s3, s57, 0
	v_writelane_b32 v254, s2, 11
	v_mov_b32_e32 v187, 0x3c0881c4
	v_mov_b32_e32 v188, 0xbab64f3b
	v_writelane_b32 v254, s3, 12
	s_add_u32 s2, s56, 0xe1100
	s_addc_u32 s3, s57, 0
	v_writelane_b32 v254, s2, 13
	v_mov_b32_e32 v189, 1
	v_mov_b32_e32 v190, 12
	v_writelane_b32 v254, s3, 14
	s_add_u32 s2, s56, 0xe1200
	s_addc_u32 s3, s57, 0
	v_writelane_b32 v254, s2, 15
	v_mov_b32_e32 v191, 0x7f800000
	v_mov_b32_e32 v192, 0x80
	v_writelane_b32 v254, s3, 16
	s_add_u32 s2, s56, 0xe1300
	s_addc_u32 s3, s57, 0
	v_writelane_b32 v254, s2, 17
	s_cmp_eq_u32 s6, 15
	v_mov_b32_e32 v193, 0x42800000
	v_writelane_b32 v254, s3, 18
	s_cselect_b64 s[2:3], -1, 0
	v_writelane_b32 v254, s2, 19
	s_cmp_eq_u32 s6, 14
	v_not_b32_e32 v194, 63
	v_writelane_b32 v254, s3, 20
	s_cselect_b64 s[2:3], -1, 0
	v_writelane_b32 v254, s2, 21
	s_cmp_eq_u32 s6, 13
	v_not_b32_e32 v195, 31
	v_writelane_b32 v254, s3, 22
	s_cselect_b64 s[2:3], -1, 0
	v_writelane_b32 v254, s2, 23
	s_cmp_eq_u32 s6, 12
	v_mov_b32_e32 v196, 0x7fc00000
	v_writelane_b32 v254, s3, 24
	s_cselect_b64 s[2:3], -1, 0
	v_writelane_b32 v254, s2, 25
	s_cmp_eq_u32 s6, 11
	s_movk_i32 s93, 0x2000
	v_writelane_b32 v254, s3, 26
	s_cselect_b64 s[2:3], -1, 0
	v_writelane_b32 v254, s2, 27
	s_cmp_eq_u32 s6, 10
	s_mov_b32 s79, 0x10000
	v_writelane_b32 v254, s3, 28
	s_cselect_b64 s[2:3], -1, 0
	v_writelane_b32 v254, s2, 29
	s_cmp_eq_u32 s6, 9
	s_movk_i32 s65, 0x6000
	v_writelane_b32 v254, s3, 30
	s_cselect_b64 s[2:3], -1, 0
	v_writelane_b32 v254, s2, 31
	s_cmp_eq_u32 s6, 8
	s_mov_b32 s69, 0x18000
	v_writelane_b32 v254, s3, 32
	s_cselect_b64 s[2:3], -1, 0
	v_writelane_b32 v254, s2, 33
	s_cmp_eq_u32 s6, 7
	s_mov_b32 s71, 0xc000
	v_writelane_b32 v254, s3, 34
	s_cselect_b64 s[2:3], -1, 0
	v_writelane_b32 v254, s2, 35
	s_cmp_eq_u32 s6, 6
	s_mov_b32 s92, 0xbfb8aa3b
	v_writelane_b32 v254, s3, 36
	s_cselect_b64 s[2:3], -1, 0
	v_writelane_b32 v254, s2, 37
	s_cmp_eq_u32 s6, 5
	s_movk_i32 s15, 0x3fff
	v_writelane_b32 v254, s3, 38
	s_cselect_b64 s[2:3], -1, 0
	v_writelane_b32 v254, s2, 39
	s_cmp_eq_u32 s6, 4
	s_movk_i32 s21, 0x1800
	v_writelane_b32 v254, s3, 40
	s_cselect_b64 s[2:3], -1, 0
	v_writelane_b32 v254, s2, 41
	s_cmp_eq_u32 s6, 3
	s_mov_b32 s8, 0x800000
	v_writelane_b32 v254, s3, 42
	s_cselect_b64 s[2:3], -1, 0
	v_writelane_b32 v254, s2, 43
	s_cmp_eq_u32 s6, 2
	s_movk_i32 s83, 0x84
	v_writelane_b32 v254, s3, 44
	s_cselect_b64 s[2:3], -1, 0
	v_writelane_b32 v254, s2, 45
	s_cmp_eq_u32 s6, 1
	s_mov_b32 s13, 0xb680
	v_writelane_b32 v254, s3, 46
	s_cselect_b64 s[2:3], -1, 0
	v_writelane_b32 v254, s2, 47
	s_cmp_eq_u32 s6, 0
	s_movk_i32 s9, 0x219f
	v_writelane_b32 v254, s3, 48
	s_cselect_b64 s[2:3], -1, 0
	v_writelane_b32 v254, s2, 49
	s_mov_b32 s82, 0x5e00000
	s_movk_i32 s30, 0xb00
	v_writelane_b32 v254, s3, 50
	s_lshl_b32 s2, s6, 8
	s_add_u32 s0, s0, s2
	s_addc_u32 s1, s1, 0
	s_add_u32 s2, s0, 0x1400
	s_addc_u32 s3, s1, 0
	v_writelane_b32 v254, s2, 51
	s_add_u32 s0, s0, 0x2400
	s_addc_u32 s1, s1, 0
	v_writelane_b32 v254, s3, 52
	v_writelane_b32 v254, s0, 53
	s_movk_i32 s31, 0x5800
	s_mov_b32 s96, 0x42ce8ed0
	v_writelane_b32 v254, s1, 54
	s_movk_i32 s0, 0x3ff
	v_and_or_b32 v0, v0, s0, v1
	s_add_u32 s0, s56, 0xe3400
	s_addc_u32 s1, s57, 0
	v_writelane_b32 v254, s0, 55
	v_mbcnt_lo_u32_b32 v1, -1, 0
	v_mbcnt_hi_u32_b32 v173, -1, v1
	v_writelane_b32 v254, s1, 56
	s_add_u32 s0, s56, 0xe3500
	s_addc_u32 s1, s57, 0
	v_writelane_b32 v254, s0, 57
	v_mov_b32_e32 v1, 0
	s_mov_b32 s97, 0xc2b17218
	v_writelane_b32 v254, s1, 58
	s_add_i32 s0, 0, 0xffff6040
	v_writelane_b32 v254, s0, 59
	s_add_i32 s0, 0, 0xffff9608
	v_writelane_b32 v254, s0, 60
	s_add_i32 s0, 0, 0xffff8208
	v_writelane_b32 v254, s0, 61
	s_add_i32 s0, 0, 0x20000
	v_writelane_b32 v254, s0, 62
	s_add_i32 s0, 0, 0x20004
	v_writelane_b32 v254, s0, 63
	v_cmp_eq_u32_e64 s[0:1], 0, v0
	s_mov_b32 s19, 0
	v_writelane_b32 v255, s19, 62
	s_mov_b64 s[22:23], 0x80
	v_writelane_b32 v255, s0, 0
	s_mov_b64 s[24:25], 0x100
	s_mov_b64 s[28:29], 0x200
	v_writelane_b32 v255, s1, 1
	v_writelane_b32 v255, s78, 2
	v_writelane_b32 v255, s90, 3
	s_mov_b32 s20, 0xbf1b4598
	s_mov_b32 s64, 0x3e6d3388
	v_writelane_b32 v255, s91, 4
	v_writelane_b32 v255, s94, 5
	s_mov_b32 s68, 0x3f07dc22
	s_mov_b32 s26, 0x3f35f0e3
	v_writelane_b32 v255, s95, 6
	v_writelane_b32 v255, s56, 7
	s_mov_b32 s12, 0xbe11a98e
	s_mov_b32 s38, 0x3e027906
	v_writelane_b32 v255, s57, 8
	v_writelane_b32 v255, s58, 9
	v_writelane_b32 v255, s59, 10
	v_writelane_b32 v255, s18, 11
	v_writelane_b32 v255, s36, 12
	s_mov_b32 s70, 0xbf38aa3b
	s_nop 0
	v_writelane_b32 v255, s37, 13
	v_writelane_b32 v255, s60, 14
	s_nop 1
	v_writelane_b32 v255, s61, 15
	v_writelane_b32 v255, s62, 16
	s_nop 1
	v_writelane_b32 v255, s63, 17
	v_writelane_b32 v255, s66, 18
	s_nop 1
	v_writelane_b32 v255, s67, 19
	v_writelane_b32 v255, s72, 20
	s_nop 1
	v_writelane_b32 v255, s73, 21
	v_writelane_b32 v255, s76, 22
	s_nop 1
	v_writelane_b32 v255, s77, 23
	v_writelane_b32 v255, s80, 24
	s_nop 1
	v_writelane_b32 v255, s81, 25
	v_writelane_b32 v255, s84, 26
	s_nop 1
	v_writelane_b32 v255, s85, 27
	v_writelane_b32 v255, s86, 28
	s_nop 1
	v_writelane_b32 v255, s87, 29
	v_writelane_b32 v255, s88, 30
	s_nop 1
	v_writelane_b32 v255, s89, 31
	s_branch .LBB0_11

; template <class Epi, class Sched, bool ALIGN_EPI = false, bool SP2 = false>
; __device__ __forceinline__ void gemm_phase(PG8_LAS unsigned char* lds, const Gemm g, const Sched& S, const Epi& E, const int tid_in) {
;     const int tid = tid_in, wid = __builtin_amdgcn_readfirstlane(tid >> 6), lane = tid & 63, wr = wid >> 2, wc = wid & 3, fr = lane & 15, fq = lane >> 4;
;     const int K = g.K, nt = K / BK;
;     unsigned voffA[2], voffB[2];
; #pragma unroll
;     for (int i = 0; i < 2; ++i) { int R, C; stage_rc(tid * 16 + i * 8192, R, C); const int Rb = Epi::PERM ? ((R & ~31) + perm32(R & 31)) : R;
;         voffA[i] = (unsigned)(R * K + C) * 2u; voffB[i] = (unsigned)(Rb * K + C) * 2u; }
;     const size_t kstep = (size_t)(BK * 2);
;     const size_t hstep = (size_t)HALF * K * 2;
;     const size_t tstep = 2 * hstep;
;     const unsigned ldsw = (unsigned)wid * 1024u;
;     const int aoff = lds_byte(wr * 64 + fr, fq * 8), boff = lds_byte(wc * 32 + fr, fq * 8);
; __global__ void __launch_bounds__(512, 2) mega_fwd(Args a_) {
;     ...
;                 const bf16_t* GT = (const bf16_t*)(ws + WS_GT); float* MF = (float*)(ws + WS_K);
;                 OpMerge<0> o0{GT, MF, H}; run_gemm(ti, lds, (const bf16_t*)(ws + WS_GU), (const bf16_t*)(ws + WS_WA), Mr, 1024, 1024, o0);
;                 OpMerge<1> o1{GT, MF, H}; run_gemm(ti, lds, (const bf16_t*)(ws + WS_Q), (const bf16_t*)(ws + WS_WB), Mr, 1024, 1024, o1);
;                 OpMerge<2> o2{GT, MF, H}; run_gemm(ti, lds, (const bf16_t*)(ws + WS_Y1), (const bf16_t*)(ws + WS_WC), Mr, 1024, 1024, o2);
;                 if (ctx_out && ti.nblk > 64 && ti.bid >= 32) ph_wconv(a, l + 1, lds, (ti.bid - 32) * 8 + wv, (ti.nblk - 32) * 8, lane, wv, 1);
;                 else if (ctx_out && ti.nblk <= 64) ph_wconv(a, l + 1, lds, gw, ngw, lane, wv, 1);
.LBB0_162:
	s_cmp_gt_i32 s67, 5
	s_mov_b64 s[4:5], -1
	s_cbranch_scc0 .LBB0_286
	s_waitcnt vmcnt(0)
	v_bfe_i32 v3, v178, 27, 1
	v_lshlrev_b32_e32 v0, 4, v178
	v_lshrrev_b32_e32 v3, 22, v3
	v_add_u32_e32 v3, v0, v3
	v_and_b32_e32 v3, 0xfffffc00, v3
	v_sub_u32_e32 v3, v0, v3
	v_ashrrev_i32_e32 v2, 31, v178
	v_lshrrev_b32_e32 v4, 4, v3
	v_lshrrev_b32_e32 v2, 26, v2
	v_bitop3_b32 v3, v4, v3, 32 bitop3:0x6c
	v_add_u32_e32 v2, v178, v2
	v_ashrrev_i32_e32 v5, 31, v3
	v_ashrrev_i32_e32 v2, 6, v2
	v_lshrrev_b32_e32 v5, 26, v5
	v_lshlrev_b32_e32 v4, 3, v2
	v_add_u32_e32 v5, v3, v5
	v_lshlrev_b32_e32 v2, 5, v2
	v_and_b32_e32 v150, 32, v2
	v_and_b32_e32 v2, 0xc0, v5
	v_and_b32_e32 v4, -16, v4
	v_ashrrev_i32_e32 v6, 6, v5
	v_sub_u32_e32 v2, v3, v2
	v_add_u32_e32 v155, v6, v4
	v_ashrrev_i16_sdwa v2, v189, sext(v2) dst_sel:DWORD dst_unused:UNUSED_PAD src0_sel:DWORD src1_sel:BYTE_0
	v_bfe_i32 v151, v2, 0, 16
	v_lshlrev_b32_e32 v2, 1, v155
	v_lshrrev_b32_e32 v3, 2, v155
	v_and_b32_e32 v4, 3, v6
	s_mov_b32 s3, 0x7fffffe0
	v_and_b32_e32 v2, 24, v2
	v_and_b32_e32 v3, 4, v3
	v_and_or_b32 v4, v155, s3, v4
	v_add_u32_e32 v0, 0x2000, v0
	v_or3_b32 v157, v4, v3, v2
	v_ashrrev_i32_e32 v2, 31, v0
	v_lshrrev_b32_e32 v2, 22, v2
	v_add_u32_e32 v2, v0, v2
	v_ashrrev_i32_e32 v2, 10, v2
	v_mul_i32_i24_e32 v3, 0x400, v2
	v_sub_u32_e32 v0, v0, v3
	v_lshrrev_b32_e32 v3, 4, v0
	v_bitop3_b32 v0, v3, v0, 32 bitop3:0x6c
	v_ashrrev_i32_e32 v4, 31, v0
	s_load_dwordx2 s[4:5], s[74:75], 0x110
	v_lshrrev_b32_e32 v4, 26, v4
	v_lshlrev_b32_e32 v3, 3, v2
	v_add_u32_e32 v4, v0, v4
	v_lshlrev_b32_e32 v2, 5, v2
	v_and_b32_e32 v14, 32, v2
	v_and_b32_e32 v2, 0xc0, v4
	v_and_b32_e32 v3, -16, v3
	v_ashrrev_i32_e32 v5, 6, v4
	v_sub_u32_e32 v0, v0, v2
	v_add_u32_e32 v158, v5, v3
	v_ashrrev_i16_sdwa v0, v189, sext(v0) dst_sel:DWORD dst_unused:UNUSED_PAD src0_sel:DWORD src1_sel:BYTE_0
	s_waitcnt lgkmcnt(0)
	s_add_u32 s48, s4, 0x19000000
	v_bfe_i32 v15, v0, 0, 16
	v_lshlrev_b32_e32 v0, 1, v158
	v_lshrrev_b32_e32 v2, 2, v158
	v_and_b32_e32 v3, 3, v5
	s_addc_u32 s49, s5, 0
	v_and_b32_e32 v0, 24, v0
	v_and_b32_e32 v2, 4, v2
	v_and_or_b32 v3, v158, s3, v3
	s_add_u32 s50, s4, 0xca00000
	v_readlane_b32 s6, v255, 49
	v_or3_b32 v160, v3, v2, v0
	v_lshrrev_b32_e32 v0, 1, v178
	s_addc_u32 s51, s5, 0
	s_lshr_b32 s1, s6, 8
	s_lshr_b32 s18, s6, 6
	v_and_b32_e32 v149, 15, v178
	v_and_b32_e32 v152, 24, v0
	v_lshlrev_b32_e32 v148, 2, v178
	v_lshlrev_b32_e32 v153, 1, v152
	v_lshlrev_b32_e32 v0, 6, v149
	v_and_b32_e32 v2, 32, v148
	s_cmp_lt_i32 s2, s18
	s_movk_i32 s40, 0x400
	v_readfirstlane_b32 s33, v178
	v_add_u32_e32 v156, v150, v151
	v_add_u32_e32 v159, v14, v15
	s_cselect_b64 s[44:45], -1, 0
	s_cmp_lg_u32 s0, 0x100
	s_cbranch_scc1 .Lwcpre_skip
	s_cmp_lt_u32 s2, 96
	s_cbranch_scc1 .Lwcpre_skip
	s_cmp_eq_u64 s[76:77], 0
	s_cbranch_scc1 .Lwcpre_skip
	v_readlane_b32 vcc_lo, v255, 62
	s_nop 3
	s_cmp_lg_u32 vcc_lo, 0
	s_cbranch_scc1 .Lwcpre_skip
	s_mov_b32 vcc_lo, 1
	s_nop 0
	v_writelane_b32 v255, vcc_lo, 62
	s_branch .LBB0_227
.Lwcpre_skip:
	s_cmp_ge_i32 s2, s18
	v_bitop3_b32 v154, v153, v2, v0 bitop3:0x36
	s_cbranch_scc1 .LBB0_184
	s_load_dwordx2 s[4:5], s[74:75], 0x110
	v_mul_lo_u32 v0, s40, v160
	v_add_lshl_u32 v130, v0, v159, 1
	v_mul_lo_u32 v0, s40, v157
	v_add_lshl_u32 v0, v0, v156, 1
	s_waitcnt lgkmcnt(0)
	s_add_u32 s3, s4, 0x5e00000
	s_addc_u32 s10, s5, 0
	s_add_u32 s11, s4, 0x1800000
	s_addc_u32 s14, s5, 0
	s_ashr_i32 s27, s2, 31
	s_lshr_b32 s4, s27, 29
	s_add_i32 s4, s2, s4
	s_ashr_i32 s36, s33, 6
	s_ashr_i32 s41, s40, 31
	s_lshr_b32 s17, s6, 9
	s_ashr_i32 s5, s4, 3
	s_and_b32 s4, s4, -8
	s_ashr_i32 s43, s33, 8
	s_lshl_b64 s[52:53], s[40:41], 8
	s_lshl_b64 s[54:55], s[40:41], 9
	s_lshl_b32 s16, s36, 10
	s_sub_i32 s4, s2, s4
	s_or_b32 s34, s17, 1
	s_cmp_lt_i32 s4, 0
	s_cselect_b32 s6, s34, s17
	s_mul_i32 s4, s4, s6
	s_add_i32 s4, s4, s5
	s_ashr_i32 s5, s4, 31
	s_lshr_b32 s5, s5, 27
	s_add_i32 s5, s4, s5
	s_ashr_i32 s6, s5, 5
	s_lshl_b32 s6, s6, 3
	s_sub_i32 s7, s1, s6
	s_min_i32 s7, s7, 8
	s_andn2_b32 s5, s5, 31
	s_sub_i32 s35, s4, s5
	s_sext_i32_i8 s4, s7
	v_cvt_f32_i32_e32 v3, s4
	v_cvt_f32_i32_e32 v2, s35
	s_xor_b32 s5, s35, s4
	s_ashr_i32 s5, s5, 30
	v_rcp_iflag_f32_e32 v4, v3
	s_or_b32 s37, s5, 1
	v_mov_b32_e32 v131, v1
	v_mul_lo_u32 v17, s40, v155
	v_mul_f32_e32 v4, v2, v4
	v_trunc_f32_e32 v4, v4
	v_fma_f32 v2, -v4, v3, v2
	v_cvt_i32_f32_e32 v4, v4
	v_cmp_ge_f32_e64 s[4:5], |v2|, |v3|
	s_and_b64 s[4:5], s[4:5], exec
	s_cselect_b32 s4, s37, 0
	v_readfirstlane_b32 s5, v4
	s_add_i32 s42, s5, s4
	s_mul_i32 s4, s42, s7
	s_sub_i32 s4, s35, s4
	s_sext_i32_i8 s4, s4
	s_add_i32 s95, s6, s4
	s_ashr_i32 s4, s95, 31
	s_mul_i32 s4, s54, s4
	s_mul_hi_u32 s5, s54, s95
	s_add_i32 s6, s5, s4
	s_lshr_b64 s[4:5], s[40:41], 23
	s_mul_i32 s5, s4, s95
	s_add_i32 s37, s6, s5
	s_bfe_i64 s[6:7], s[42:43], 0x80000
	s_mul_i32 s5, s54, s7
	s_mul_hi_u32 s7, s54, s6
	s_add_i32 s5, s7, s5
	s_mul_i32 s4, s4, s6
	s_add_i32 s5, s5, s4
	s_mul_i32 s4, s54, s6
	s_add_u32 s4, s11, s4
	s_addc_u32 s5, s14, s5
	s_add_i32 s35, s16, 0
	s_add_i32 m0, s35, 0x10000
	s_mul_i32 s39, s54, s95
	global_load_lds_dwordx4 v0, s[4:5]
	s_add_i32 m0, s35, 0x12000
	s_add_u32 s6, s4, s52
	global_load_lds_dwordx4 v130, s[4:5]
	s_addc_u32 s7, s5, s53
	s_add_i32 m0, s35, 0x14000
	v_lshl_add_u64 v[6:7], s[6:7], 0, v[0:1]
	global_load_lds_dwordx4 v0, s[6:7]
	s_add_i32 m0, s35, 0x16000
	v_lshl_add_u64 v[8:9], s[6:7], 0, v[130:131]
	global_load_lds_dwordx4 v130, s[6:7]
	s_add_u32 s6, s3, s39
	s_addc_u32 s7, s10, s37
	s_add_i32 s37, s35, 0x2000
	v_mul_lo_u32 v16, s40, v158
	v_add_lshl_u32 v134, v17, v156, 1
	s_mov_b32 m0, s35
	s_add_u32 s56, s6, s52
	v_add_lshl_u32 v132, v16, v159, 1
	global_load_lds_dwordx4 v134, s[6:7]
	s_mov_b32 m0, s37
	s_addc_u32 s57, s7, s53
	s_add_i32 s39, s35, 0x4000
	global_load_lds_dwordx4 v132, s[6:7]
	s_mov_b32 m0, s39
	s_add_i32 s62, s35, 0x6000
	global_load_lds_dwordx4 v134, s[56:57]
	s_mov_b32 m0, s62
	v_mov_b32_e32 v135, v1
	global_load_lds_dwordx4 v132, s[56:57]
	v_mov_b32_e32 v133, v1
	s_cmp_eq_u32 s43, 1
	s_mov_b32 s86, s67
	v_lshl_add_u64 v[2:3], s[4:5], 0, v[0:1]
	v_lshl_add_u64 v[4:5], s[4:5], 0, v[130:131]
	v_lshl_add_u64 v[10:11], s[6:7], 0, v[134:135]
	v_lshl_add_u64 v[12:13], s[6:7], 0, v[132:133]
	s_cselect_b64 s[56:57], -1, 0
	s_cmp_lg_u32 s43, 1
	s_cbranch_scc1 .LBB0_166
	s_barrier

; __global__ void __launch_bounds__(512, 2) mega_fwd(Args a_) {
;     ...
;                 if (ctx_out && ti.nblk > 64 && ti.bid >= 32) ph_wconv(a, l + 1, lds, (ti.bid - 32) * 8 + wv, (ti.nblk - 32) * 8, lane, wv, 1);
;                 else if (ctx_out && ti.nblk <= 64) ph_wconv(a, l + 1, lds, gw, ngw, lane, wv, 1);
.LBB0_227:
	v_readlane_b32 vcc_lo, v255, 62
	s_nop 3
	s_movk_i32 vcc_hi, 95
	s_cmp_eq_u32 vcc_lo, 2
	s_cselect_b32 vcc_hi, 0x7fffffff, vcc_hi
	s_cbranch_scc0 .Lwcpre_keep
	s_mov_b32 vcc_lo, 0
	s_nop 0
	v_writelane_b32 v255, vcc_lo, 62
.Lwcpre_keep:
	s_cmp_gt_i32 s0, 64
	s_cselect_b64 s[4:5], -1, 0
	s_and_b64 s[4:5], s[76:77], s[4:5]
	s_cmp_eq_u32 s0, 0x100
	s_cselect_b32 s6, vcc_hi, 31
	s_cmp_gt_i32 s2, s6
	s_cselect_b64 s[6:7], -1, 0
	s_and_b64 s[4:5], s[4:5], s[6:7]
	v_readlane_b32 s6, v255, 50
	s_andn2_b64 vcc, exec, s[4:5]
	s_mov_b64 s[4:5], -1
	s_mov_b32 s14, s6
	v_readlane_b32 s7, v255, 51
	s_cbranch_vccz .LBB0_257
	s_cmpk_lt_i32 s0, 0x41
	s_cselect_b64 s[4:5], -1, 0
	s_and_b64 s[4:5], s[76:77], s[4:5]
	s_andn2_b64 vcc, exec, s[4:5]
	s_cbranch_vccnz .LBB0_256
	s_add_i32 s44, s62, 1
	s_cmpk_lt_i32 s14, 0x16d0
	s_mov_b64 s[4:5], -1
	s_cbranch_scc1 .LBB0_231
	s_ashr_i32 s45, s44, 31
	s_mov_b64 s[4:5], 0

; __global__ void __launch_bounds__(512, 2) mega_fwd(Args a_) {
;     ...
;                 if (ctx_out && ti.nblk > 64 && ti.bid >= 32) ph_wconv(a, l + 1, lds, (ti.bid - 32) * 8 + wv, (ti.nblk - 32) * 8, lane, wv, 1);
;                 else if (ctx_out && ti.nblk <= 64) ph_wconv(a, l + 1, lds, gw, ngw, lane, wv, 1);
;     ...
;         if (ph + 1 < ph_hi) { if (ph == ph_lo) grid.sync(); else xcd_barrier(xbar); }
.LBB0_285:
	v_readlane_b32 s4, v255, 62
	s_nop 3
	s_cmp_lg_u32 s4, 1
	s_cbranch_scc1 .Lwcpre_norm
	s_mov_b32 s4, 2
	s_nop 0
	v_writelane_b32 v255, s4, 62
	s_waitcnt vmcnt(0) lgkmcnt(0)
	s_barrier
	s_branch .LBB0_162
